# ADIFF fast loop: the 4 LDS-DMA issues per chunk moved from the busy tail-pair gaps of body 0 into the S1-chain gaps of body 1 (only 2 LDS reads there); weighted VALU spacing
# speedup vs baseline: 1.0006x; 1.0006x over previous
; __device__ __forceinline__ void diff_attn_phase(const Params& p, LAS unsigned char* lds) {
;     ...
;         auto issue = [&](int ch, int stg) {
;             const char* kg = (const char*)(kp + (tokb + 64 * ch) * ld); const char* vg = (const char*)(vp + (tokb + 64 * ch) * ld);
;             LAS unsigned char* sb = lds + stg * STG;
; #pragma unroll
;             for (int i = 0; i < 2; ++i) { unsigned o = doff[i]; asm volatile("" : "+v"(o));
;                 __builtin_amdgcn_global_load_lds((const void*)(kg + o), (LAS void*)(sb + dlds[i]), 16, 0, 0);
;                 __builtin_amdgcn_global_load_lds((const void*)(vg + o), (LAS void*)(sb + 16384 + dlds[i]), 16, 0, 0); }
;         };
;         issue(0, 0); issue(1, 1);
;         int s_cur = 0, s_nn = 2;
;         for (int ch = 0; ch < NCH; ++ch) {
;             if (ch + 1 < NCH) asm volatile("s_waitcnt vmcnt(4)" ::: "memory"); else asm volatile("s_waitcnt vmcnt(0)" ::: "memory");
;             __builtin_amdgcn_s_barrier(); asm volatile("" ::: "memory");
;             if (ch + 2 < NCH) issue(ch + 2, s_nn);
;             const LAS unsigned char* Ksb = lds + s_cur * STG; const LAS unsigned char* Vsb = Ksb + 16384;
;             s_nn = s_cur; s_cur = (s_cur == 2) ? 0 : s_cur + 1;
; #pragma clang loop unroll(disable)
;             for (int u = 0; u < 2; ++u) {
;                 const LAS unsigned char* Ku = Ksb + u * 8192; const LAS unsigned char* Vu = Vsb + u * 8192;
;                 int kxl = kx, vb0l = vb0, vb1l = vb1; asm volatile("" : "+v"(kxl), "+v"(vb0l), "+v"(vb1l));
;                 bf16x8 kf[4];
; #pragma unroll
;                 for (int ks = 0; ks < 4; ++ks) kf[ks] = *(const LAS bf16x8*)(Ku + kbase + (kxl ^ (32 * ks)));
;                 bf16x8 P[2][2];
; #pragma unroll
;                 for (int r = 0; r < 2; ++r) {
;                     f32x16 S;
; #pragma unroll
;                     for (int i = 0; i < 16; ++i) S[i] = 0.f;
; #pragma unroll
;                     for (int ks = 0; ks < 4; ++ks) S = __builtin_amdgcn_mfma_f32_32x32x16_bf16(kf[ks], qf[r][ks], S, 0, 0, 0);
;                     S = __builtin_amdgcn_mfma_f32_32x32x16_bf16(kone, qm[r], S, 0, 0, 0);
; #pragma unroll
;                     for (int i = 0; i < 16; ++i) S[i] = __builtin_amdgcn_exp2f(S[i]);
;                     l[r] += sum16(S);
;                     P[r][0] = pack8(S, 0); P[r][1] = pack8(S, 8);
;                 }
; #pragma unroll
.Lfb_w1F:
	s_barrier
	s_add_i32 s2, s29, 1
	s_and_b32 s2, s2, 3
	s_mov_b32 s37, 0x8000
	s_cmp_eq_u32 s2, 0
	s_cselect_b32 s37, 0xfffe8000, s37
	v_add_u32_e32 v1, s37, v1
	s_add_i32 s2, s29, 3
	s_lshl_b32 s10, s2, 6
	s_add_u32 s10, s26, s10
	s_addc_u32 s11, s27, 0
	s_lshl_b64 s[10:11], s[10:11], 13
	s_add_u32 s42, s25, s10
	s_addc_u32 s43, s28, s11
	s_add_u32 s10, s22, s10
	s_addc_u32 s11, s23, s11
	s_and_b32 s2, s2, 3
	s_lshl_b32 s2, s2, 15
	s_add_i32 s2, s2, s34
	s_waitcnt lgkmcnt(6)
	v_mfma_f32_32x32x16_bf16 v[114:129], v[198:201], v[222:225], v[114:129]
	v_exp_f32_e32 v130, v130
	v_exp_f32_e32 v131, v131
	v_mfma_f32_32x32x16_bf16 v[50:65], v[198:201], v[226:229], v[50:65]
	v_add_u32_e32 v198, v246, v1
	ds_read_b128 v[198:201], v198
	v_exp_f32_e32 v132, v132
	v_exp_f32_e32 v133, v133
	s_waitcnt lgkmcnt(5)
	v_mfma_f32_32x32x16_bf16 v[98:113], v[202:205], v[222:225], v[98:113]
	v_add_f32_e32 v212, v212, v130
	v_add_f32_e32 v212, v212, v131
	v_add_f32_e32 v212, v212, v132
	v_add_f32_e32 v212, v212, v133
	v_mfma_f32_32x32x16_bf16 v[34:49], v[202:205], v[226:229], v[34:49]
	v_xad_u32 v202, v246, 32, v1
	ds_read_b128 v[202:205], v202
	v_exp_f32_e32 v134, v134
	v_exp_f32_e32 v135, v135
	s_waitcnt lgkmcnt(4)
	v_mfma_f32_32x32x16_bf16 v[82:97], v[208:211], v[222:225], v[82:97]
	v_exp_f32_e32 v136, v136
	v_exp_f32_e32 v137, v137
	v_mfma_f32_32x32x16_bf16 v[18:33], v[208:211], v[226:229], v[18:33]
	v_xad_u32 v208, v246, 64, v1
	ds_read_b128 v[208:211], v208
	v_add_f32_e32 v212, v212, v134
	v_add_f32_e32 v212, v212, v135
	v_add_f32_e32 v212, v212, v136
	v_add_f32_e32 v212, v212, v137
	s_waitcnt lgkmcnt(3)
	v_mfma_f32_32x32x16_bf16 v[66:81], v[230:233], v[222:225], v[66:81]
	v_cvt_pk_bf16_f32 v214, v146, v147
	v_cvt_pk_bf16_f32 v215, v148, v149
	v_cvt_pk_bf16_f32 v216, v150, v151
	v_cvt_pk_bf16_f32 v217, v152, v153
	v_cvt_pk_bf16_f32 v218, v130, v131
	v_cvt_pk_bf16_f32 v219, v132, v133
	v_cvt_pk_bf16_f32 v220, v134, v135
	v_cvt_pk_bf16_f32 v221, v136, v137
	v_cvt_pk_bf16_f32 v222, v154, v155
	v_cvt_pk_bf16_f32 v223, v156, v157
	v_cvt_pk_bf16_f32 v224, v158, v159
	v_cvt_pk_bf16_f32 v225, v160, v161
	v_mfma_f32_32x32x16_bf16 v[2:17], v[230:233], v[226:229], v[2:17]
	v_xad_u32 v230, v246, s47, v1
	ds_read_b128 v[230:233], v230
	s_waitcnt lgkmcnt(3)
	v_mfma_f32_32x32x16_bf16 v[146:161], v[198:201], v[166:169], 0
	v_exp_f32_e32 v138, v138
	v_exp_f32_e32 v139, v139
	v_exp_f32_e32 v140, v140
	v_exp_f32_e32 v141, v141
	s_waitcnt lgkmcnt(2)
	v_mfma_f32_32x32x16_bf16 v[146:161], v[202:205], v[170:173], v[146:161]
	v_add_f32_e32 v212, v212, v138
	v_add_f32_e32 v212, v212, v139
	v_add_f32_e32 v212, v212, v140
	v_add_f32_e32 v212, v212, v141
	v_exp_f32_e32 v142, v142
	v_exp_f32_e32 v143, v143
	s_waitcnt lgkmcnt(1)
	v_mfma_f32_32x32x16_bf16 v[146:161], v[208:211], v[174:177], v[146:161]
	v_exp_f32_e32 v144, v144
	v_exp_f32_e32 v145, v145
	v_add_f32_e32 v212, v212, v142
	v_add_f32_e32 v212, v212, v143
	s_waitcnt lgkmcnt(0)
	v_mfma_f32_32x32x16_bf16 v[146:161], v[230:233], v[178:181], v[146:161]
	v_add_f32_e32 v212, v212, v144
	v_add_f32_e32 v212, v212, v145
	v_cvt_pk_bf16_f32 v226, v138, v139
	v_cvt_pk_bf16_f32 v227, v140, v141
	v_cvt_pk_bf16_f32 v228, v142, v143
	v_cvt_pk_bf16_f32 v229, v144, v145
	v_mfma_f32_32x32x16_bf16 v[130:145], v[198:201], v[182:185], 0
	ds_read_b64_tr_b16 v[198:199], v234 offset:24576
	ds_read_b64_tr_b16 v[200:201], v235 offset:24576
	s_cmpk_gt_u32 s29, 0x7c
	s_cbranch_scc1 .Lfb_nd0F
	s_mov_b32 m0, s2
	s_nop 0
	global_load_lds_dwordx4 v241, s[42:43]
.Lfb_nd0F:
	v_mfma_f32_32x32x16_bf16 v[130:145], v[202:205], v[186:189], v[130:145]
	ds_read_b64_tr_b16 v[202:203], v237 offset:24576
	ds_read_b64_tr_b16 v[204:205], v236 offset:24576
	v_exp_f32_e32 v146, v146
	v_exp_f32_e32 v147, v147
	v_exp_f32_e32 v148, v148
	s_cmpk_gt_u32 s29, 0x7c
	s_cbranch_scc1 .Lfb_nd1F
	s_add_i32 s35, s2, 0x4000
	s_mov_b32 m0, s35
	s_nop 0
	global_load_lds_dwordx4 v241, s[10:11]
.Lfb_nd1F:
	v_mfma_f32_32x32x16_bf16 v[130:145], v[208:211], v[190:193], v[130:145]
	ds_read_b64_tr_b16 v[208:209], v238 offset:24576
	ds_read_b64_tr_b16 v[210:211], v239 offset:24576
	v_exp_f32_e32 v149, v149
	v_add_f32_e32 v213, v213, v146
	v_add_f32_e32 v213, v213, v147
	v_add_f32_e32 v213, v213, v148
	s_cmpk_gt_u32 s29, 0x7c
	s_cbranch_scc1 .Lfb_nd2F
	s_add_i32 s35, s2, 0x2000
	s_mov_b32 m0, s35
	s_nop 0
	global_load_lds_dwordx4 v243, s[42:43]
; __device__ __forceinline__ void diff_attn_phase(const Params& p, LAS unsigned char* lds) {
;     ...
;         auto issue = [&](int ch, int stg) {
;             const char* kg = (const char*)(kp + (tokb + 64 * ch) * ld); const char* vg = (const char*)(vp + (tokb + 64 * ch) * ld);
;             LAS unsigned char* sb = lds + stg * STG;
; #pragma unroll
;             for (int i = 0; i < 2; ++i) { unsigned o = doff[i]; asm volatile("" : "+v"(o));
;                 __builtin_amdgcn_global_load_lds((const void*)(kg + o), (LAS void*)(sb + dlds[i]), 16, 0, 0);
;                 __builtin_amdgcn_global_load_lds((const void*)(vg + o), (LAS void*)(sb + 16384 + dlds[i]), 16, 0, 0); }
;         };
;         issue(0, 0); issue(1, 1);
;         int s_cur = 0, s_nn = 2;
;         for (int ch = 0; ch < NCH; ++ch) {
;             if (ch + 1 < NCH) asm volatile("s_waitcnt vmcnt(4)" ::: "memory"); else asm volatile("s_waitcnt vmcnt(0)" ::: "memory");
;             __builtin_amdgcn_s_barrier(); asm volatile("" ::: "memory");
;             if (ch + 2 < NCH) issue(ch + 2, s_nn);
;             const LAS unsigned char* Ksb = lds + s_cur * STG; const LAS unsigned char* Vsb = Ksb + 16384;
;             s_nn = s_cur; s_cur = (s_cur == 2) ? 0 : s_cur + 1;
; #pragma clang loop unroll(disable)
;             for (int u = 0; u < 2; ++u) {
;                 const LAS unsigned char* Ku = Ksb + u * 8192; const LAS unsigned char* Vu = Vsb + u * 8192;
;                 int kxl = kx, vb0l = vb0, vb1l = vb1; asm volatile("" : "+v"(kxl), "+v"(vb0l), "+v"(vb1l));
;                 bf16x8 kf[4];
; #pragma unroll
;                 for (int ks = 0; ks < 4; ++ks) kf[ks] = *(const LAS bf16x8*)(Ku + kbase + (kxl ^ (32 * ks)));
;                 bf16x8 P[2][2];
; #pragma unroll
;                 for (int r = 0; r < 2; ++r) {
;                     f32x16 S;
; #pragma unroll
;                     for (int i = 0; i < 16; ++i) S[i] = 0.f;
; #pragma unroll
;                     for (int ks = 0; ks < 4; ++ks) S = __builtin_amdgcn_mfma_f32_32x32x16_bf16(kf[ks], qf[r][ks], S, 0, 0, 0);
;                     S = __builtin_amdgcn_mfma_f32_32x32x16_bf16(kone, qm[r], S, 0, 0, 0);
; #pragma unroll
;                     for (int i = 0; i < 16; ++i) S[i] = __builtin_amdgcn_exp2f(S[i]);
;                     l[r] += sum16(S);
;                     P[r][0] = pack8(S, 0); P[r][1] = pack8(S, 8);
;                 }
; #pragma unroll
.Lfb_nd2F:
	v_mfma_f32_32x32x16_bf16 v[130:145], v[230:233], v[194:197], v[130:145]
	ds_read_b64_tr_b16 v[230:231], v250 offset:24576
	ds_read_b64_tr_b16 v[232:233], v251 offset:24576
	v_add_f32_e32 v213, v213, v149
	v_exp_f32_e32 v150, v150
	v_exp_f32_e32 v151, v151
	s_cmpk_gt_u32 s29, 0x7c
	s_cbranch_scc1 .Lfb_nd3F
	s_add_i32 s35, s2, 0x6000
	s_mov_b32 m0, s35
	s_nop 0
	global_load_lds_dwordx4 v243, s[10:11]
.Lfb_nd3F:
	s_waitcnt lgkmcnt(6)
	v_mfma_f32_32x32x16_bf16 v[114:129], v[198:201], v[214:217], v[114:129]
	v_exp_f32_e32 v152, v152
	v_exp_f32_e32 v153, v153
	v_mfma_f32_32x32x16_bf16 v[50:65], v[198:201], v[218:221], v[50:65]
	ds_read_b64_tr_b16 v[198:199], v234 offset:28672
	ds_read_b64_tr_b16 v[200:201], v235 offset:28672
	v_add_f32_e32 v213, v213, v150
	v_add_f32_e32 v213, v213, v151
	v_add_f32_e32 v213, v213, v152
	v_add_f32_e32 v213, v213, v153
	s_waitcnt lgkmcnt(6)
	v_mfma_f32_32x32x16_bf16 v[98:113], v[202:205], v[214:217], v[98:113]
	v_exp_f32_e32 v154, v154
	v_exp_f32_e32 v155, v155
	v_mfma_f32_32x32x16_bf16 v[34:49], v[202:205], v[218:221], v[34:49]
	ds_read_b64_tr_b16 v[202:203], v237 offset:28672
	ds_read_b64_tr_b16 v[204:205], v236 offset:28672
	v_exp_f32_e32 v156, v156
	v_exp_f32_e32 v157, v157
	s_waitcnt lgkmcnt(6)
	v_mfma_f32_32x32x16_bf16 v[82:97], v[208:211], v[214:217], v[82:97]
	v_add_f32_e32 v213, v213, v154
	v_add_f32_e32 v213, v213, v155
	v_add_f32_e32 v213, v213, v156
	v_add_f32_e32 v213, v213, v157
	v_mfma_f32_32x32x16_bf16 v[18:33], v[208:211], v[218:221], v[18:33]
	ds_read_b64_tr_b16 v[208:209], v238 offset:28672
	ds_read_b64_tr_b16 v[210:211], v239 offset:28672
	v_exp_f32_e32 v158, v158
	v_exp_f32_e32 v159, v159
	s_waitcnt lgkmcnt(6)
	v_mfma_f32_32x32x16_bf16 v[66:81], v[230:233], v[214:217], v[66:81]
	v_exp_f32_e32 v160, v160
	v_exp_f32_e32 v161, v161
	v_mfma_f32_32x32x16_bf16 v[2:17], v[230:233], v[218:221], v[2:17]
	ds_read_b64_tr_b16 v[230:231], v250 offset:28672
	ds_read_b64_tr_b16 v[232:233], v251 offset:28672
	v_add_f32_e32 v213, v213, v158
	v_add_f32_e32 v213, v213, v159
	v_add_f32_e32 v213, v213, v160
	v_add_f32_e32 v213, v213, v161
	v_add_u32_e32 v234, s37, v234
	v_add_u32_e32 v235, s37, v235
	v_add_u32_e32 v237, s37, v237
	v_add_u32_e32 v236, s37, v236
	v_add_u32_e32 v238, s37, v238
	v_add_u32_e32 v239, s37, v239
	v_add_u32_e32 v250, s37, v250
	v_add_u32_e32 v251, s37, v251
	s_waitcnt lgkmcnt(6)
	v_mfma_f32_32x32x16_bf16 v[114:129], v[198:201], v[222:225], v[114:129]
	v_exp_f32_e32 v130, v130
	v_exp_f32_e32 v131, v131
	v_mfma_f32_32x32x16_bf16 v[50:65], v[198:201], v[226:229], v[50:65]
	v_add_u32_e32 v198, v246, v1
	ds_read_b128 v[198:201], v198 offset:8192
	v_exp_f32_e32 v132, v132
	v_exp_f32_e32 v133, v133
	s_waitcnt lgkmcnt(5)
	v_mfma_f32_32x32x16_bf16 v[98:113], v[202:205], v[222:225], v[98:113]
	v_add_f32_e32 v212, v212, v130
	v_add_f32_e32 v212, v212, v131
	v_add_f32_e32 v212, v212, v132
	v_add_f32_e32 v212, v212, v133
	v_mfma_f32_32x32x16_bf16 v[34:49], v[202:205], v[226:229], v[34:49]
	v_xad_u32 v202, v246, 32, v1
	ds_read_b128 v[202:205], v202 offset:8192
	v_exp_f32_e32 v134, v134
	v_exp_f32_e32 v135, v135
	s_waitcnt lgkmcnt(4)
	v_mfma_f32_32x32x16_bf16 v[82:97], v[208:211], v[222:225], v[82:97]
	v_exp_f32_e32 v136, v136
	v_exp_f32_e32 v137, v137
	v_mfma_f32_32x32x16_bf16 v[18:33], v[208:211], v[226:229], v[18:33]
	v_xad_u32 v208, v246, 64, v1
	ds_read_b128 v[208:211], v208 offset:8192
	v_add_f32_e32 v212, v212, v134
	v_add_f32_e32 v212, v212, v135
	v_add_f32_e32 v212, v212, v136
	v_add_f32_e32 v212, v212, v137
	s_waitcnt lgkmcnt(3)
	v_mfma_f32_32x32x16_bf16 v[66:81], v[230:233], v[222:225], v[66:81]
	v_cvt_pk_bf16_f32 v214, v146, v147
	v_cvt_pk_bf16_f32 v215, v148, v149
	v_cvt_pk_bf16_f32 v216, v150, v151
	v_cvt_pk_bf16_f32 v217, v152, v153
	v_cvt_pk_bf16_f32 v218, v130, v131
	v_cvt_pk_bf16_f32 v219, v132, v133
	v_cvt_pk_bf16_f32 v220, v134, v135
	v_cvt_pk_bf16_f32 v221, v136, v137
	v_cvt_pk_bf16_f32 v222, v154, v155
	v_cvt_pk_bf16_f32 v223, v156, v157
	v_cvt_pk_bf16_f32 v224, v158, v159
	v_cvt_pk_bf16_f32 v225, v160, v161
	v_mfma_f32_32x32x16_bf16 v[2:17], v[230:233], v[226:229], v[2:17]
	v_xad_u32 v230, v246, s47, v1
	ds_read_b128 v[230:233], v230 offset:8192
	s_add_i32 s29, s29, 1
	s_branch .Lfb_loopF
